# attention row-max chain: 30 compiler pad s_nop 0 between inline-asm v_max3_f32 ops removed (no hazard between non-transcendental VALU ops)
# baseline (speedup 1.0000x reference)
.LBB0_943:
	v_max3_f32 v180, v96, v97, v80
	v_max3_f32 v202, v98, v99, v81
	s_cmp_eq_u32 s62, 63
	v_max3_f32 v180, v180, v82, v83
	v_max3_f32 v202, v202, v102, v103
	s_cselect_b64 s[16:17], -1, 0
	v_max3_f32 v180, v180, v100, v101
	v_max3_f32 v202, v202, v86, v87
	s_cmp_lg_u32 s62, 63
	v_max3_f32 v180, v180, v84, v85
	v_max3_f32 v202, v202, v106, v107
	v_max3_f32 v180, v180, v104, v105
	v_max3_f32 v202, v202, v90, v91
	v_max3_f32 v180, v180, v88, v89
	v_max3_f32 v202, v202, v110, v111
	v_max3_f32 v180, v180, v108, v109
	v_max3_f32 v202, v202, v94, v95
	v_max3_f32 v180, v180, v92, v93
	v_max3_f32 v180, v180, v202, v202
	v_mov_b32_e32 v202, v180
	v_mov_b32_e32 v203, v180
	s_nop 1
	v_permlane32_swap_b32_e32 v202, v203
	v_max3_f32 v210, v202, v203, v180
	s_cbranch_scc0 .LBB0_959
	v_cmp_lt_f32_e32 vcc, s54, v210
	s_mov_b64 s[42:43], 0
	s_mov_b64 s[40:41], 0
	s_cbranch_vccz .LBB0_950
	v_max_f32_e32 v180, v210, v210
	v_max_f32_e32 v180, 0, v180
	s_mov_b64 s[40:41], -1

.LBB0_954:
	v_max3_f32 v180, v96, v97, v80
	v_max3_f32 v202, v98, v99, v81
	v_max3_f32 v180, v180, v82, v83
	v_max3_f32 v202, v202, v102, v103
	v_max3_f32 v180, v180, v100, v101
	v_max3_f32 v202, v202, v86, v87
	v_max3_f32 v180, v180, v84, v85
	v_max3_f32 v202, v202, v106, v107
	v_max3_f32 v180, v180, v104, v105
	v_max3_f32 v202, v202, v90, v91
	v_max3_f32 v180, v180, v88, v89
	v_max3_f32 v202, v202, v110, v111
	v_max3_f32 v180, v180, v108, v109
	v_max3_f32 v202, v202, v94, v95
	v_max3_f32 v180, v180, v92, v93
	v_max3_f32 v180, v180, v202, v202
	v_mov_b32_e32 v202, v180
	v_mov_b32_e32 v203, v180
	s_nop 1
	v_permlane32_swap_b32_e32 v202, v203
	v_max3_f32 v180, v202, v203, v180
	s_nop 0
	v_cmp_lt_f32_e32 vcc, s54, v180
	s_cbranch_vccz .LBB0_956
	v_max_f32_e32 v64, v180, v180
	v_max_f32_e32 v66, 0, v64
	v_exp_f32_e64 v180, -v66
	v_add_f32_e32 v209, v209, v66
	v_xor_b32_e32 v64, 0x80000000, v209
	v_pk_add_f32 v[96:97], v[96:97], v[66:67] op_sel_hi:[1,0] neg_lo:[0,1] neg_hi:[0,1]
	v_pk_add_f32 v[80:81], v[80:81], v[66:67] op_sel_hi:[1,0] neg_lo:[0,1] neg_hi:[0,1]
	v_pk_add_f32 v[98:99], v[98:99], v[66:67] op_sel_hi:[1,0] neg_lo:[0,1] neg_hi:[0,1]
	v_pk_add_f32 v[82:83], v[82:83], v[66:67] op_sel_hi:[1,0] neg_lo:[0,1] neg_hi:[0,1]
	v_pk_add_f32 v[100:101], v[100:101], v[66:67] op_sel_hi:[1,0] neg_lo:[0,1] neg_hi:[0,1]
	v_pk_add_f32 v[84:85], v[84:85], v[66:67] op_sel_hi:[1,0] neg_lo:[0,1] neg_hi:[0,1]
	v_pk_add_f32 v[102:103], v[102:103], v[66:67] op_sel_hi:[1,0] neg_lo:[0,1] neg_hi:[0,1]
	v_pk_add_f32 v[86:87], v[86:87], v[66:67] op_sel_hi:[1,0] neg_lo:[0,1] neg_hi:[0,1]
	v_pk_add_f32 v[104:105], v[104:105], v[66:67] op_sel_hi:[1,0] neg_lo:[0,1] neg_hi:[0,1]
	v_pk_add_f32 v[88:89], v[88:89], v[66:67] op_sel_hi:[1,0] neg_lo:[0,1] neg_hi:[0,1]
	v_pk_add_f32 v[106:107], v[106:107], v[66:67] op_sel_hi:[1,0] neg_lo:[0,1] neg_hi:[0,1]
	v_pk_add_f32 v[90:91], v[90:91], v[66:67] op_sel_hi:[1,0] neg_lo:[0,1] neg_hi:[0,1]
	v_pk_add_f32 v[108:109], v[108:109], v[66:67] op_sel_hi:[1,0] neg_lo:[0,1] neg_hi:[0,1]
	v_pk_add_f32 v[92:93], v[92:93], v[66:67] op_sel_hi:[1,0] neg_lo:[0,1] neg_hi:[0,1]
	v_pk_add_f32 v[110:111], v[110:111], v[66:67] op_sel_hi:[1,0] neg_lo:[0,1] neg_hi:[0,1]
	v_pk_add_f32 v[94:95], v[94:95], v[66:67] op_sel_hi:[1,0] neg_lo:[0,1] neg_hi:[0,1]
	v_pk_mul_f32 v[62:63], v[62:63], v[180:181] op_sel_hi:[1,0]
	v_pk_mul_f32 v[60:61], v[60:61], v[180:181] op_sel_hi:[1,0]
	v_pk_mul_f32 v[58:59], v[58:59], v[180:181] op_sel_hi:[1,0]
	v_pk_mul_f32 v[56:57], v[56:57], v[180:181] op_sel_hi:[1,0]
	v_pk_mul_f32 v[54:55], v[54:55], v[180:181] op_sel_hi:[1,0]
	v_pk_mul_f32 v[52:53], v[52:53], v[180:181] op_sel_hi:[1,0]
	v_pk_mul_f32 v[50:51], v[50:51], v[180:181] op_sel_hi:[1,0]
	v_pk_mul_f32 v[48:49], v[48:49], v[180:181] op_sel_hi:[1,0]
	v_pk_mul_f32 v[46:47], v[46:47], v[180:181] op_sel_hi:[1,0]
	v_pk_mul_f32 v[44:45], v[44:45], v[180:181] op_sel_hi:[1,0]
	v_pk_mul_f32 v[42:43], v[42:43], v[180:181] op_sel_hi:[1,0]
	v_pk_mul_f32 v[40:41], v[40:41], v[180:181] op_sel_hi:[1,0]
	v_pk_mul_f32 v[38:39], v[38:39], v[180:181] op_sel_hi:[1,0]
	v_pk_mul_f32 v[36:37], v[36:37], v[180:181] op_sel_hi:[1,0]
	v_pk_mul_f32 v[34:35], v[34:35], v[180:181] op_sel_hi:[1,0]
	v_pk_mul_f32 v[32:33], v[32:33], v[180:181] op_sel_hi:[1,0]
	v_pk_mul_f32 v[30:31], v[30:31], v[180:181] op_sel_hi:[1,0]
	v_pk_mul_f32 v[28:29], v[28:29], v[180:181] op_sel_hi:[1,0]
	v_pk_mul_f32 v[26:27], v[26:27], v[180:181] op_sel_hi:[1,0]
	v_pk_mul_f32 v[24:25], v[24:25], v[180:181] op_sel_hi:[1,0]
	v_pk_mul_f32 v[22:23], v[22:23], v[180:181] op_sel_hi:[1,0]
	v_pk_mul_f32 v[20:21], v[20:21], v[180:181] op_sel_hi:[1,0]
	v_pk_mul_f32 v[18:19], v[18:19], v[180:181] op_sel_hi:[1,0]
	v_pk_mul_f32 v[16:17], v[16:17], v[180:181] op_sel_hi:[1,0]
	v_pk_mul_f32 v[14:15], v[14:15], v[180:181] op_sel_hi:[1,0]
	v_pk_mul_f32 v[12:13], v[12:13], v[180:181] op_sel_hi:[1,0]
	v_pk_mul_f32 v[10:11], v[10:11], v[180:181] op_sel_hi:[1,0]
	v_pk_mul_f32 v[8:9], v[8:9], v[180:181] op_sel_hi:[1,0]
	v_pk_mul_f32 v[6:7], v[6:7], v[180:181] op_sel_hi:[1,0]
	v_pk_mul_f32 v[4:5], v[4:5], v[180:181] op_sel_hi:[1,0]
	v_pk_mul_f32 v[2:3], v[2:3], v[180:181] op_sel_hi:[1,0]
	v_pk_mul_f32 v[0:1], v[0:1], v[180:181] op_sel_hi:[1,0]
	v_mov_b32_e32 v65, v64
	v_mov_b32_e32 v66, v64
	v_mov_b32_e32 v67, v64
	v_mov_b32_e32 v68, v64
	v_mov_b32_e32 v69, v64
	v_mov_b32_e32 v70, v64
	v_mov_b32_e32 v71, v64
	v_mov_b32_e32 v72, v64
	v_mov_b32_e32 v73, v64
	v_mov_b32_e32 v74, v64
	v_mov_b32_e32 v75, v64
	v_mov_b32_e32 v76, v64
	v_mov_b32_e32 v77, v64
	v_mov_b32_e32 v78, v64
	v_mov_b32_e32 v79, v64
	v_mul_f32_e32 v206, v206, v180

.LBB0_965:
	v_max3_f32 v180, v96, v97, v80
	v_max3_f32 v202, v98, v99, v81
	s_cmp_eq_u32 s40, 63
	v_max3_f32 v180, v180, v82, v83
	v_max3_f32 v202, v202, v102, v103
	s_cselect_b64 s[16:17], -1, 0
	v_max3_f32 v180, v180, v100, v101
	v_max3_f32 v202, v202, v86, v87
	s_cmp_lg_u32 s40, 63
	v_max3_f32 v180, v180, v84, v85
	v_max3_f32 v202, v202, v106, v107
	v_max3_f32 v180, v180, v104, v105
	v_max3_f32 v202, v202, v90, v91
	v_max3_f32 v180, v180, v88, v89
	v_max3_f32 v202, v202, v110, v111
	v_max3_f32 v180, v180, v108, v109
	v_max3_f32 v202, v202, v94, v95
	v_max3_f32 v180, v180, v92, v93
	v_max3_f32 v180, v180, v202, v202
	v_mov_b32_e32 v202, v180
	v_mov_b32_e32 v203, v180
	s_nop 1
	v_permlane32_swap_b32_e32 v202, v203
	v_max3_f32 v211, v202, v203, v180
	s_cbranch_scc0 .LBB0_981
	v_cmp_lt_f32_e32 vcc, s54, v211
	s_mov_b64 s[34:35], 0
	s_mov_b64 s[30:31], 0
	s_cbranch_vccz .LBB0_972
	v_max_f32_e32 v180, v211, v211
	v_max_f32_e32 v180, 0, v180
	s_mov_b64 s[30:31], -1

.LBB0_976:
	v_max3_f32 v180, v96, v97, v80
	v_max3_f32 v202, v98, v99, v81
	v_max3_f32 v180, v180, v82, v83
	v_max3_f32 v202, v202, v102, v103
	v_max3_f32 v180, v180, v100, v101
	v_max3_f32 v202, v202, v86, v87
	v_max3_f32 v180, v180, v84, v85
	v_max3_f32 v202, v202, v106, v107
	v_max3_f32 v180, v180, v104, v105
	v_max3_f32 v202, v202, v90, v91
	v_max3_f32 v180, v180, v88, v89
	v_max3_f32 v202, v202, v110, v111
	v_max3_f32 v180, v180, v108, v109
	v_max3_f32 v202, v202, v94, v95
	v_max3_f32 v180, v180, v92, v93
	v_max3_f32 v180, v180, v202, v202
	v_mov_b32_e32 v202, v180
	v_mov_b32_e32 v203, v180
	s_nop 1
	v_permlane32_swap_b32_e32 v202, v203
	v_max3_f32 v180, v202, v203, v180
	s_nop 0
	v_cmp_lt_f32_e32 vcc, s54, v180
	s_cbranch_vccz .LBB0_978
	v_max_f32_e32 v64, v180, v180
	v_max_f32_e32 v66, 0, v64
	v_exp_f32_e64 v180, -v66
	v_add_f32_e32 v210, v210, v66
	v_xor_b32_e32 v64, 0x80000000, v210
	v_pk_add_f32 v[96:97], v[96:97], v[66:67] op_sel_hi:[1,0] neg_lo:[0,1] neg_hi:[0,1]
	v_pk_add_f32 v[80:81], v[80:81], v[66:67] op_sel_hi:[1,0] neg_lo:[0,1] neg_hi:[0,1]
	v_pk_add_f32 v[98:99], v[98:99], v[66:67] op_sel_hi:[1,0] neg_lo:[0,1] neg_hi:[0,1]
	v_pk_add_f32 v[82:83], v[82:83], v[66:67] op_sel_hi:[1,0] neg_lo:[0,1] neg_hi:[0,1]
	v_pk_add_f32 v[100:101], v[100:101], v[66:67] op_sel_hi:[1,0] neg_lo:[0,1] neg_hi:[0,1]
	v_pk_add_f32 v[84:85], v[84:85], v[66:67] op_sel_hi:[1,0] neg_lo:[0,1] neg_hi:[0,1]
	v_pk_add_f32 v[102:103], v[102:103], v[66:67] op_sel_hi:[1,0] neg_lo:[0,1] neg_hi:[0,1]
	v_pk_add_f32 v[86:87], v[86:87], v[66:67] op_sel_hi:[1,0] neg_lo:[0,1] neg_hi:[0,1]
	v_pk_add_f32 v[104:105], v[104:105], v[66:67] op_sel_hi:[1,0] neg_lo:[0,1] neg_hi:[0,1]
	v_pk_add_f32 v[88:89], v[88:89], v[66:67] op_sel_hi:[1,0] neg_lo:[0,1] neg_hi:[0,1]
	v_pk_add_f32 v[106:107], v[106:107], v[66:67] op_sel_hi:[1,0] neg_lo:[0,1] neg_hi:[0,1]
	v_pk_add_f32 v[90:91], v[90:91], v[66:67] op_sel_hi:[1,0] neg_lo:[0,1] neg_hi:[0,1]
	v_pk_add_f32 v[108:109], v[108:109], v[66:67] op_sel_hi:[1,0] neg_lo:[0,1] neg_hi:[0,1]
	v_pk_add_f32 v[92:93], v[92:93], v[66:67] op_sel_hi:[1,0] neg_lo:[0,1] neg_hi:[0,1]
	v_pk_add_f32 v[110:111], v[110:111], v[66:67] op_sel_hi:[1,0] neg_lo:[0,1] neg_hi:[0,1]
	v_pk_add_f32 v[94:95], v[94:95], v[66:67] op_sel_hi:[1,0] neg_lo:[0,1] neg_hi:[0,1]
	v_pk_mul_f32 v[62:63], v[62:63], v[180:181] op_sel_hi:[1,0]
	v_pk_mul_f32 v[60:61], v[60:61], v[180:181] op_sel_hi:[1,0]
	v_pk_mul_f32 v[58:59], v[58:59], v[180:181] op_sel_hi:[1,0]
	v_pk_mul_f32 v[56:57], v[56:57], v[180:181] op_sel_hi:[1,0]
	v_pk_mul_f32 v[54:55], v[54:55], v[180:181] op_sel_hi:[1,0]
	v_pk_mul_f32 v[52:53], v[52:53], v[180:181] op_sel_hi:[1,0]
	v_pk_mul_f32 v[50:51], v[50:51], v[180:181] op_sel_hi:[1,0]
	v_pk_mul_f32 v[48:49], v[48:49], v[180:181] op_sel_hi:[1,0]
	v_pk_mul_f32 v[46:47], v[46:47], v[180:181] op_sel_hi:[1,0]
	v_pk_mul_f32 v[44:45], v[44:45], v[180:181] op_sel_hi:[1,0]
	v_pk_mul_f32 v[42:43], v[42:43], v[180:181] op_sel_hi:[1,0]
	v_pk_mul_f32 v[40:41], v[40:41], v[180:181] op_sel_hi:[1,0]
	v_pk_mul_f32 v[38:39], v[38:39], v[180:181] op_sel_hi:[1,0]
	v_pk_mul_f32 v[36:37], v[36:37], v[180:181] op_sel_hi:[1,0]
	v_pk_mul_f32 v[34:35], v[34:35], v[180:181] op_sel_hi:[1,0]
	v_pk_mul_f32 v[32:33], v[32:33], v[180:181] op_sel_hi:[1,0]
	v_pk_mul_f32 v[30:31], v[30:31], v[180:181] op_sel_hi:[1,0]
	v_pk_mul_f32 v[28:29], v[28:29], v[180:181] op_sel_hi:[1,0]
	v_pk_mul_f32 v[26:27], v[26:27], v[180:181] op_sel_hi:[1,0]
	v_pk_mul_f32 v[24:25], v[24:25], v[180:181] op_sel_hi:[1,0]
	v_pk_mul_f32 v[22:23], v[22:23], v[180:181] op_sel_hi:[1,0]
	v_pk_mul_f32 v[20:21], v[20:21], v[180:181] op_sel_hi:[1,0]
	v_pk_mul_f32 v[18:19], v[18:19], v[180:181] op_sel_hi:[1,0]
	v_pk_mul_f32 v[16:17], v[16:17], v[180:181] op_sel_hi:[1,0]
	v_pk_mul_f32 v[14:15], v[14:15], v[180:181] op_sel_hi:[1,0]
	v_pk_mul_f32 v[12:13], v[12:13], v[180:181] op_sel_hi:[1,0]
	v_pk_mul_f32 v[10:11], v[10:11], v[180:181] op_sel_hi:[1,0]
	v_pk_mul_f32 v[8:9], v[8:9], v[180:181] op_sel_hi:[1,0]
	v_pk_mul_f32 v[6:7], v[6:7], v[180:181] op_sel_hi:[1,0]
	v_pk_mul_f32 v[4:5], v[4:5], v[180:181] op_sel_hi:[1,0]
	v_pk_mul_f32 v[2:3], v[2:3], v[180:181] op_sel_hi:[1,0]
	v_pk_mul_f32 v[0:1], v[0:1], v[180:181] op_sel_hi:[1,0]
	v_mov_b32_e32 v65, v64
	v_mov_b32_e32 v66, v64
	v_mov_b32_e32 v67, v64
	v_mov_b32_e32 v68, v64
	v_mov_b32_e32 v69, v64
	v_mov_b32_e32 v70, v64
	v_mov_b32_e32 v71, v64
	v_mov_b32_e32 v72, v64
	v_mov_b32_e32 v73, v64
	v_mov_b32_e32 v74, v64
	v_mov_b32_e32 v75, v64
	v_mov_b32_e32 v76, v64
	v_mov_b32_e32 v77, v64
	v_mov_b32_e32 v78, v64
	v_mov_b32_e32 v79, v64
	v_mul_f32_e32 v206, v206, v180
